# attention steady loop: cross-half max combine (mov+nop+permlane+max) moved into the rare rescale blocks; branch decides on per-lane partial max
# speedup vs baseline: 1.0393x; 1.0018x over previous
.LBB0_381:
	v_add_u32_e32 v183, s20, v209
	ds_read_b64_tr_b16 v[178:179], v183 offset:24576
	ds_read_b64_tr_b16 v[180:181], v183 offset:25088
	s_waitcnt lgkmcnt(9)
	v_mfma_f32_32x32x16_bf16 v[98:113], v[174:177], v[142:145], v[34:49]
	v_add_f32_e32 v82, v66, v67
	v_add_f32_e32 v82, v68, v82
	v_add_f32_e32 v82, v69, v82
	v_add_f32_e32 v82, v70, v82
	v_add_f32_e32 v82, v71, v82
	v_cvt_pk_bf16_f32 v138, v66, v67
	v_cvt_pk_bf16_f32 v139, v68, v69
	ds_read_b64_tr_b16 v[174:175], v183 offset:28672
	ds_read_b64_tr_b16 v[176:177], v183 offset:29184
	v_add_f32_e32 v66, v72, v82
	s_waitcnt lgkmcnt(10)
	v_mfma_f32_32x32x16_bf16 v[82:97], v[170:173], v[142:145], v[34:49]
	v_add_f32_e32 v66, v73, v66
	v_add_f32_e32 v66, v74, v66
	v_add_f32_e32 v114, v75, v66
	v_cvt_pk_bf16_f32 v140, v70, v71
	v_cvt_pk_bf16_f32 v141, v72, v73
	ds_read_b64_tr_b16 v[66:67], v183 offset:25600
	ds_read_b64_tr_b16 v[68:69], v183 offset:26112
	s_waitcnt lgkmcnt(11)
	v_mfma_f32_32x32x16_bf16 v[98:113], v[166:169], v[134:137], v[98:113]
	v_add_f32_e32 v70, v76, v114
	v_add_f32_e32 v70, v77, v70
	v_add_f32_e32 v70, v78, v70
	v_add_f32_e32 v114, v79, v70
	v_cvt_pk_bf16_f32 v130, v74, v75
	v_cvt_pk_bf16_f32 v131, v76, v77
	ds_read_b64_tr_b16 v[70:71], v183 offset:29696
	ds_read_b64_tr_b16 v[72:73], v183 offset:30208
	s_waitcnt lgkmcnt(12)
	v_mfma_f32_32x32x16_bf16 v[82:97], v[162:165], v[134:137], v[82:97]
	v_add_f32_e32 v74, v80, v114
	v_add_f32_e32 v74, v81, v74
	v_add_f32_e32 v74, v50, v74
	v_add_f32_e32 v114, v51, v74
	v_cvt_pk_bf16_f32 v132, v78, v79
	v_cvt_pk_bf16_f32 v133, v80, v81
	ds_read_b64_tr_b16 v[74:75], v183 offset:26624
	ds_read_b64_tr_b16 v[76:77], v183 offset:27136
	s_waitcnt lgkmcnt(13)
	v_mfma_f32_32x32x16_bf16 v[98:113], v[158:161], v[126:129], v[98:113]
	v_add_f32_e32 v78, v52, v114
	v_add_f32_e32 v78, v53, v78
	v_add_f32_e32 v78, v54, v78
	v_add_f32_e32 v78, v55, v78
	v_cvt_pk_bf16_f32 v122, v50, v51
	v_cvt_pk_bf16_f32 v123, v52, v53
	ds_read_b64_tr_b16 v[50:51], v183 offset:30720
	ds_read_b64_tr_b16 v[52:53], v183 offset:31232
	s_waitcnt lgkmcnt(14)
	v_mfma_f32_32x32x16_bf16 v[82:97], v[154:157], v[126:129], v[82:97]
	v_add_f32_e32 v78, v56, v78
	v_add_f32_e32 v78, v57, v78
	v_add_f32_e32 v78, v58, v78
	v_add_f32_e32 v78, v59, v78
	v_cvt_pk_bf16_f32 v124, v54, v55
	v_cvt_pk_bf16_f32 v125, v56, v57
	ds_read_b64_tr_b16 v[54:55], v183 offset:27648
	ds_read_b64_tr_b16 v[56:57], v183 offset:28160
	s_waitcnt lgkmcnt(14)
	v_mfma_f32_32x32x16_bf16 v[98:113], v[150:153], v[118:121], v[98:113]
	v_add_f32_e32 v78, v60, v78
	v_add_f32_e32 v78, v61, v78
	v_add_f32_e32 v78, v62, v78
	v_add_f32_e32 v78, v63, v78
	v_cvt_pk_bf16_f32 v114, v58, v59
	v_cvt_pk_bf16_f32 v115, v60, v61
	ds_read_b64_tr_b16 v[58:59], v183 offset:31744
	ds_read_b64_tr_b16 v[60:61], v183 offset:32256
	v_mfma_f32_32x32x16_bf16 v[82:97], v[146:149], v[118:121], v[82:97]
	v_add_f32_e32 v78, v64, v78
	v_add_f32_e32 v78, v65, v78
	v_cvt_pk_bf16_f32 v116, v62, v63
	v_cvt_pk_bf16_f32 v117, v64, v65
	s_add_i32 s20, s72, s29
	s_mov_b32 s21, m0
	s_mov_b32 m0, s20
	s_nop 0
	global_load_lds_dwordx4 v226, s[98:99]
	s_mov_b32 m0, s21
	s_add_i32 s20, s36, s30
	s_mov_b32 s21, m0
	s_mov_b32 m0, s20
	s_nop 0
	global_load_lds_dwordx4 v228, s[100:101]
	s_mov_b32 m0, s21
	v_max_f32_e32 v62, v98, v99
	v_max3_f32 v63, v100, v101, v83
	v_max3_f32 v62, v62, v82, v84
	v_max3_f32 v62, v62, v85, v102
	v_max3_f32 v63, v63, v104, v105
	v_max3_f32 v62, v62, v103, v86
	v_max3_f32 v63, v63, v88, v89
	v_max3_f32 v62, v62, v87, v106
	v_max3_f32 v63, v63, v108, v109
	v_max3_f32 v62, v62, v107, v90
	v_max3_f32 v63, v63, v92, v93
	v_max3_f32 v62, v62, v91, v110
	v_max3_f32 v63, v63, v112, v113
	v_max3_f32 v62, v62, v111, v94
	v_max3_f32 v63, v63, v96, v97
	v_max3_f32 v62, v62, v95, v63
	v_cmp_lt_f32_e32 vcc, s69, v62
	s_cmp_lg_u64 vcc, 0
	v_add_f32_e32 v183, v194, v78
	s_cselect_b64 s[20:21], -1, 0
	s_cbranch_vccnz .LBB0_389

.LBB0_384:
	s_add_i32 s20, s36, 0x2000
	s_cmpk_lg_i32 s36, 0x4000
	s_cselect_b32 s35, s20, 0
	v_add_u32_e32 v194, s72, v209
	ds_read_b64_tr_b16 v[150:151], v194 offset:24576
	ds_read_b64_tr_b16 v[152:153], v194 offset:25088
	s_waitcnt lgkmcnt(9)
	v_mfma_f32_32x32x16_bf16 v[66:81], v[62:65], v[142:145], v[34:49]
	v_add_f32_e32 v50, v98, v99
	v_add_f32_e32 v50, v100, v50
	v_add_f32_e32 v50, v101, v50
	v_add_f32_e32 v50, v102, v50
	v_add_f32_e32 v50, v103, v50
	v_cvt_pk_bf16_f32 v138, v98, v99
	v_cvt_pk_bf16_f32 v139, v100, v101
	ds_read_b64_tr_b16 v[146:147], v194 offset:28672
	ds_read_b64_tr_b16 v[148:149], v194 offset:29184
	v_add_f32_e32 v50, v104, v50
	v_add_f32_e32 v50, v105, v50
	v_add_f32_e32 v50, v106, v50
	v_add_f32_e32 v114, v107, v50
	s_waitcnt lgkmcnt(10)
	v_mfma_f32_32x32x16_bf16 v[50:65], v[174:177], v[142:145], v[34:49]
	v_cvt_pk_bf16_f32 v140, v102, v103
	v_cvt_pk_bf16_f32 v141, v104, v105
	ds_read_b64_tr_b16 v[98:99], v194 offset:25600
	ds_read_b64_tr_b16 v[100:101], v194 offset:26112
	s_waitcnt lgkmcnt(11)
	v_mfma_f32_32x32x16_bf16 v[66:81], v[178:181], v[134:137], v[66:81]
	v_add_f32_e32 v102, v108, v114
	v_add_f32_e32 v102, v109, v102
	v_add_f32_e32 v102, v110, v102
	v_add_f32_e32 v114, v111, v102
	v_cvt_pk_bf16_f32 v130, v106, v107
	v_cvt_pk_bf16_f32 v131, v108, v109
	ds_read_b64_tr_b16 v[102:103], v194 offset:29696
	ds_read_b64_tr_b16 v[104:105], v194 offset:30208
	s_waitcnt lgkmcnt(12)
	v_mfma_f32_32x32x16_bf16 v[50:65], v[170:173], v[134:137], v[50:65]
	v_add_f32_e32 v106, v112, v114
	v_add_f32_e32 v106, v113, v106
	v_add_f32_e32 v106, v82, v106
	v_add_f32_e32 v114, v83, v106
	v_cvt_pk_bf16_f32 v132, v110, v111
	v_cvt_pk_bf16_f32 v133, v112, v113
	ds_read_b64_tr_b16 v[106:107], v194 offset:26624
	ds_read_b64_tr_b16 v[108:109], v194 offset:27136
	s_waitcnt lgkmcnt(13)
	v_mfma_f32_32x32x16_bf16 v[66:81], v[166:169], v[126:129], v[66:81]
	v_add_f32_e32 v110, v84, v114
	v_add_f32_e32 v110, v85, v110
	v_add_f32_e32 v110, v86, v110
	v_add_f32_e32 v110, v87, v110
	v_cvt_pk_bf16_f32 v122, v82, v83
	v_cvt_pk_bf16_f32 v123, v84, v85
	ds_read_b64_tr_b16 v[82:83], v194 offset:30720
	ds_read_b64_tr_b16 v[84:85], v194 offset:31232
	s_waitcnt lgkmcnt(14)
	v_mfma_f32_32x32x16_bf16 v[50:65], v[162:165], v[126:129], v[50:65]
	v_add_f32_e32 v110, v88, v110
	v_add_f32_e32 v110, v89, v110
	v_add_f32_e32 v110, v90, v110
	v_add_f32_e32 v110, v91, v110
	v_cvt_pk_bf16_f32 v124, v86, v87
	v_cvt_pk_bf16_f32 v125, v88, v89
	ds_read_b64_tr_b16 v[86:87], v194 offset:27648
	ds_read_b64_tr_b16 v[88:89], v194 offset:28160
	s_waitcnt lgkmcnt(14)
	v_mfma_f32_32x32x16_bf16 v[66:81], v[158:161], v[118:121], v[66:81]
	v_add_f32_e32 v110, v92, v110
	v_add_f32_e32 v110, v93, v110
	v_add_f32_e32 v110, v94, v110
	v_add_f32_e32 v110, v95, v110
	v_cvt_pk_bf16_f32 v114, v90, v91
	v_cvt_pk_bf16_f32 v115, v92, v93
	ds_read_b64_tr_b16 v[90:91], v194 offset:31744
	ds_read_b64_tr_b16 v[92:93], v194 offset:32256
	v_mfma_f32_32x32x16_bf16 v[50:65], v[154:157], v[118:121], v[50:65]
	v_add_f32_e32 v110, v96, v110
	v_add_f32_e32 v110, v97, v110
	v_cvt_pk_bf16_f32 v116, v94, v95
	v_cvt_pk_bf16_f32 v117, v96, v97
	s_add_i32 s20, s36, s29
	s_mov_b32 s21, m0
	s_mov_b32 m0, s20
	s_nop 0
	global_load_lds_dwordx4 v227, s[98:99]
	s_mov_b32 m0, s21
	s_add_i32 s20, s35, s30
	s_mov_b32 s21, m0
	s_mov_b32 m0, s20
	s_nop 0
	global_load_lds_dwordx4 v229, s[100:101]
	s_mov_b32 m0, s21
	v_max_f32_e32 v94, v66, v67
	v_max3_f32 v95, v68, v69, v51
	v_max3_f32 v94, v94, v50, v52
	v_max3_f32 v94, v94, v53, v70
	v_max3_f32 v95, v95, v72, v73
	v_max3_f32 v94, v94, v71, v54
	v_max3_f32 v95, v95, v56, v57
	v_max3_f32 v94, v94, v55, v74
	v_max3_f32 v95, v95, v76, v77
	v_max3_f32 v94, v94, v75, v58
	v_max3_f32 v95, v95, v60, v61
	v_max3_f32 v94, v94, v59, v78
	v_max3_f32 v95, v95, v80, v81
	v_max3_f32 v94, v94, v79, v62
	v_max3_f32 v95, v95, v64, v65
	v_max3_f32 v94, v94, v63, v95
	v_cmp_lt_f32_e32 vcc, s69, v94
	s_cmp_lg_u64 vcc, 0
	v_add_f32_e32 v194, v183, v110
	s_cselect_b64 s[20:21], -1, 0
	s_cbranch_vccnz .LBB0_392

.LBB0_389:
	v_mov_b32_e32 v63, v62
	s_nop 1
	v_permlane32_swap_b32_e32 v62, v63
	v_max_f32_e32 v62, v62, v63
	v_max_f32_e32 v34, v62, v62
	v_max_f32_e32 v62, 0, v34
	v_exp_f32_e64 v63, -v62
	v_add_f32_e32 v207, v207, v62
	v_xor_b32_e32 v34, 0x80000000, v207
	v_mov_b32_e32 v35, v34
	v_mov_b32_e32 v36, v34
	v_mov_b32_e32 v37, v34
	v_mov_b32_e32 v38, v34
	v_mov_b32_e32 v39, v34
	v_mov_b32_e32 v40, v34
	v_mov_b32_e32 v41, v34
	v_mov_b32_e32 v42, v34
	v_mov_b32_e32 v43, v34
	v_mov_b32_e32 v44, v34
	v_mov_b32_e32 v45, v34
	v_mov_b32_e32 v46, v34
	v_mov_b32_e32 v47, v34
	v_mov_b32_e32 v48, v34
	v_mov_b32_e32 v49, v34
	s_and_saveexec_b64 s[22:23], s[4:5]
	ds_write_b32 v206, v63 offset:49152
	s_or_b64 exec, exec, s[22:23]
	v_sub_f32_e32 v113, v113, v62
	v_sub_f32_e32 v112, v112, v62
	v_sub_f32_e32 v111, v111, v62
	v_sub_f32_e32 v110, v110, v62
	v_sub_f32_e32 v109, v109, v62
	v_sub_f32_e32 v108, v108, v62
	v_sub_f32_e32 v107, v107, v62
	v_sub_f32_e32 v106, v106, v62
	v_sub_f32_e32 v105, v105, v62
	v_sub_f32_e32 v104, v104, v62
	v_sub_f32_e32 v103, v103, v62
	v_sub_f32_e32 v102, v102, v62
	v_sub_f32_e32 v101, v101, v62
	v_sub_f32_e32 v100, v100, v62
	v_sub_f32_e32 v99, v99, v62
	v_sub_f32_e32 v98, v98, v62
	v_sub_f32_e32 v97, v97, v62
	v_sub_f32_e32 v96, v96, v62
	v_sub_f32_e32 v95, v95, v62
	v_sub_f32_e32 v94, v94, v62
	v_sub_f32_e32 v93, v93, v62
	v_sub_f32_e32 v92, v92, v62
	v_sub_f32_e32 v91, v91, v62
	v_sub_f32_e32 v90, v90, v62
	v_sub_f32_e32 v89, v89, v62
	v_sub_f32_e32 v88, v88, v62
	v_sub_f32_e32 v87, v87, v62
	v_sub_f32_e32 v86, v86, v62
	v_sub_f32_e32 v85, v85, v62
	v_sub_f32_e32 v84, v84, v62
	v_sub_f32_e32 v83, v83, v62
	v_sub_f32_e32 v82, v82, v62
	v_mul_f32_e32 v183, v183, v63
	s_branch .LBB0_382
.LBB0_392:
	v_mov_b32_e32 v95, v94
	s_nop 1
	v_permlane32_swap_b32_e32 v94, v95
	v_max_f32_e32 v94, v94, v95
	v_max_f32_e32 v34, v94, v94
	v_max_f32_e32 v94, 0, v34
	v_exp_f32_e64 v95, -v94
	v_add_f32_e32 v207, v207, v94
	v_xor_b32_e32 v34, 0x80000000, v207
	v_mov_b32_e32 v35, v34
	v_mov_b32_e32 v36, v34
	v_mov_b32_e32 v37, v34
	v_mov_b32_e32 v38, v34
	v_mov_b32_e32 v39, v34
	v_mov_b32_e32 v40, v34
	v_mov_b32_e32 v41, v34
	v_mov_b32_e32 v42, v34
	v_mov_b32_e32 v43, v34
	v_mov_b32_e32 v44, v34
	v_mov_b32_e32 v45, v34
	v_mov_b32_e32 v46, v34
	v_mov_b32_e32 v47, v34
	v_mov_b32_e32 v48, v34
	v_mov_b32_e32 v49, v34
	s_and_saveexec_b64 s[22:23], s[4:5]
	ds_write_b32 v206, v95 offset:49152
	s_or_b64 exec, exec, s[22:23]
	v_sub_f32_e32 v81, v81, v94
	v_sub_f32_e32 v80, v80, v94
	v_sub_f32_e32 v79, v79, v94
	v_sub_f32_e32 v78, v78, v94
	v_sub_f32_e32 v77, v77, v94
	v_sub_f32_e32 v76, v76, v94
	v_sub_f32_e32 v75, v75, v94
	v_sub_f32_e32 v74, v74, v94
	v_sub_f32_e32 v73, v73, v94
	v_sub_f32_e32 v72, v72, v94
	v_sub_f32_e32 v71, v71, v94
	v_sub_f32_e32 v70, v70, v94
	v_sub_f32_e32 v69, v69, v94
	v_sub_f32_e32 v68, v68, v94
	v_sub_f32_e32 v67, v67, v94
	v_sub_f32_e32 v66, v66, v94
	v_sub_f32_e32 v65, v65, v94
	v_sub_f32_e32 v64, v64, v94
	v_sub_f32_e32 v63, v63, v94
	v_sub_f32_e32 v62, v62, v94
	v_sub_f32_e32 v61, v61, v94
	v_sub_f32_e32 v60, v60, v94
	v_sub_f32_e32 v59, v59, v94
	v_sub_f32_e32 v58, v58, v94
	v_sub_f32_e32 v57, v57, v94
	v_sub_f32_e32 v56, v56, v94
	v_sub_f32_e32 v55, v55, v94
	v_sub_f32_e32 v54, v54, v94
	v_sub_f32_e32 v53, v53, v94
	v_sub_f32_e32 v52, v52, v94
	v_sub_f32_e32 v51, v51, v94
	v_sub_f32_e32 v50, v50, v94
	v_mul_f32_e32 v194, v194, v95
	s_branch .LBB0_385

.LBB0_938:
	v_lshl_or_b32 v142, s24, 7, v146
	v_lshl_add_u32 v148, s26, 8, v144
	v_ashrrev_i32_e32 v143, 31, v142
	v_mov_b64_e32 v[140:141], s[52:53]
	v_lshlrev_b64 v[142:143], 1, v[142:143]
	v_readlane_b32 s78, v252, 4
	s_andn2_b64 vcc, exec, s[8:9]
	v_readlane_b32 s79, v252, 5
	s_mov_b32 s98, 0xbfb8aa3b
	v_pk_mul_f32 v[152:153], v[126:127], s[98:99] op_sel_hi:[1,0]
	v_pk_mul_f32 v[154:155], v[128:129], s[98:99] op_sel_hi:[1,0]
	v_pk_mul_f32 v[156:157], v[118:119], s[98:99] op_sel_hi:[1,0]
	v_pk_mul_f32 v[158:159], v[120:121], s[98:99] op_sel_hi:[1,0]
	v_exp_f32_e32 v152, v152
	v_exp_f32_e32 v153, v153
	v_exp_f32_e32 v154, v154
	v_exp_f32_e32 v155, v155
	v_exp_f32_e32 v156, v156
	v_exp_f32_e32 v157, v157
	v_exp_f32_e32 v158, v158
	v_exp_f32_e32 v159, v159
	v_mov_b32_e32 v170, v148
	v_mad_i64_i32 v[168:169], s[4:5], v170, s70, v[140:141]
	v_pk_add_f32 v[152:153], v[152:153], 1.0 op_sel_hi:[1,0]
	v_pk_add_f32 v[154:155], v[154:155], 1.0 op_sel_hi:[1,0]
	v_pk_add_f32 v[156:157], v[156:157], 1.0 op_sel_hi:[1,0]
	v_pk_add_f32 v[158:159], v[158:159], 1.0 op_sel_hi:[1,0]
	v_rcp_f32_e32 v152, v152
	v_rcp_f32_e32 v153, v153
	v_rcp_f32_e32 v154, v154
	v_rcp_f32_e32 v155, v155
	v_rcp_f32_e32 v156, v156
	v_rcp_f32_e32 v157, v157
	v_rcp_f32_e32 v158, v158
	v_rcp_f32_e32 v159, v159
	v_lshl_add_u64 v[168:169], v[168:169], 0, v[142:143]
	v_pk_mul_f32 v[152:153], v[126:127], v[152:153]
	v_pk_mul_f32 v[154:155], v[128:129], v[154:155]
	v_pk_mul_f32 v[156:157], v[118:119], v[156:157]
	v_pk_mul_f32 v[158:159], v[120:121], v[158:159]
	v_pk_mul_f32 v[152:153], v[152:153], v[122:123]
	v_pk_mul_f32 v[154:155], v[154:155], v[124:125]
	v_pk_mul_f32 v[156:157], v[156:157], v[114:115]
	v_pk_mul_f32 v[158:159], v[158:159], v[116:117]
	v_cvt_pk_bf16_f32 v160, v152, v153
	v_cvt_pk_bf16_f32 v161, v154, v155
	v_cvt_pk_bf16_f32 v162, v156, v157
	v_cvt_pk_bf16_f32 v163, v158, v159
	global_store_dwordx4 v[168:169], v[160:163], off
	v_pk_mul_f32 v[152:153], v[110:111], s[98:99] op_sel_hi:[1,0]
	v_pk_mul_f32 v[154:155], v[112:113], s[98:99] op_sel_hi:[1,0]
	v_pk_mul_f32 v[156:157], v[102:103], s[98:99] op_sel_hi:[1,0]
	v_pk_mul_f32 v[158:159], v[104:105], s[98:99] op_sel_hi:[1,0]
	v_exp_f32_e32 v152, v152
	v_exp_f32_e32 v153, v153
	v_exp_f32_e32 v154, v154
	v_exp_f32_e32 v155, v155
	v_exp_f32_e32 v156, v156
	v_exp_f32_e32 v157, v157
	v_exp_f32_e32 v158, v158
	v_exp_f32_e32 v159, v159
	v_add_u32_e32 v170, 0x10, v148
	v_mad_i64_i32 v[168:169], s[4:5], v170, s70, v[140:141]
	v_pk_add_f32 v[152:153], v[152:153], 1.0 op_sel_hi:[1,0]
	v_pk_add_f32 v[154:155], v[154:155], 1.0 op_sel_hi:[1,0]
	v_pk_add_f32 v[156:157], v[156:157], 1.0 op_sel_hi:[1,0]
	v_pk_add_f32 v[158:159], v[158:159], 1.0 op_sel_hi:[1,0]
	v_rcp_f32_e32 v152, v152
	v_rcp_f32_e32 v153, v153
	v_rcp_f32_e32 v154, v154
	v_rcp_f32_e32 v155, v155
	v_rcp_f32_e32 v156, v156
	v_rcp_f32_e32 v157, v157
	v_rcp_f32_e32 v158, v158
	v_rcp_f32_e32 v159, v159
	v_lshl_add_u64 v[168:169], v[168:169], 0, v[142:143]
	v_pk_mul_f32 v[152:153], v[110:111], v[152:153]
	v_pk_mul_f32 v[154:155], v[112:113], v[154:155]
	v_pk_mul_f32 v[156:157], v[102:103], v[156:157]
	v_pk_mul_f32 v[158:159], v[104:105], v[158:159]
	v_pk_mul_f32 v[152:153], v[152:153], v[106:107]
	v_pk_mul_f32 v[154:155], v[154:155], v[108:109]
	v_pk_mul_f32 v[156:157], v[156:157], v[98:99]
	v_pk_mul_f32 v[158:159], v[158:159], v[100:101]
	v_cvt_pk_bf16_f32 v164, v152, v153
	v_cvt_pk_bf16_f32 v165, v154, v155
	v_cvt_pk_bf16_f32 v166, v156, v157
	v_cvt_pk_bf16_f32 v167, v158, v159
	global_store_dwordx4 v[168:169], v[164:167], off
	v_pk_mul_f32 v[152:153], v[94:95], s[98:99] op_sel_hi:[1,0]
	v_pk_mul_f32 v[154:155], v[96:97], s[98:99] op_sel_hi:[1,0]
	v_pk_mul_f32 v[156:157], v[86:87], s[98:99] op_sel_hi:[1,0]
	v_pk_mul_f32 v[158:159], v[88:89], s[98:99] op_sel_hi:[1,0]
	v_exp_f32_e32 v152, v152
	v_exp_f32_e32 v153, v153
	v_exp_f32_e32 v154, v154
	v_exp_f32_e32 v155, v155
	v_exp_f32_e32 v156, v156
	v_exp_f32_e32 v157, v157
	v_exp_f32_e32 v158, v158
	v_exp_f32_e32 v159, v159
	v_add_u32_e32 v170, 0x20, v148
	v_mad_i64_i32 v[168:169], s[4:5], v170, s70, v[140:141]
	v_pk_add_f32 v[152:153], v[152:153], 1.0 op_sel_hi:[1,0]
	v_pk_add_f32 v[154:155], v[154:155], 1.0 op_sel_hi:[1,0]
	v_pk_add_f32 v[156:157], v[156:157], 1.0 op_sel_hi:[1,0]
	v_pk_add_f32 v[158:159], v[158:159], 1.0 op_sel_hi:[1,0]
	v_rcp_f32_e32 v152, v152
	v_rcp_f32_e32 v153, v153
	v_rcp_f32_e32 v154, v154
	v_rcp_f32_e32 v155, v155
	v_rcp_f32_e32 v156, v156
	v_rcp_f32_e32 v157, v157
	v_rcp_f32_e32 v158, v158
	v_rcp_f32_e32 v159, v159
	v_lshl_add_u64 v[168:169], v[168:169], 0, v[142:143]
	v_pk_mul_f32 v[152:153], v[94:95], v[152:153]
	v_pk_mul_f32 v[154:155], v[96:97], v[154:155]
	v_pk_mul_f32 v[156:157], v[86:87], v[156:157]
	v_pk_mul_f32 v[158:159], v[88:89], v[158:159]
	v_pk_mul_f32 v[152:153], v[152:153], v[90:91]
	v_pk_mul_f32 v[154:155], v[154:155], v[92:93]
	v_pk_mul_f32 v[156:157], v[156:157], v[82:83]
	v_pk_mul_f32 v[158:159], v[158:159], v[84:85]
	v_cvt_pk_bf16_f32 v160, v152, v153
	v_cvt_pk_bf16_f32 v161, v154, v155
	v_cvt_pk_bf16_f32 v162, v156, v157
	v_cvt_pk_bf16_f32 v163, v158, v159
	global_store_dwordx4 v[168:169], v[160:163], off
	v_pk_mul_f32 v[152:153], v[78:79], s[98:99] op_sel_hi:[1,0]
	v_pk_mul_f32 v[154:155], v[80:81], s[98:99] op_sel_hi:[1,0]
	v_pk_mul_f32 v[156:157], v[70:71], s[98:99] op_sel_hi:[1,0]
	v_pk_mul_f32 v[158:159], v[72:73], s[98:99] op_sel_hi:[1,0]
	v_exp_f32_e32 v152, v152
	v_exp_f32_e32 v153, v153
	v_exp_f32_e32 v154, v154
	v_exp_f32_e32 v155, v155
	v_exp_f32_e32 v156, v156
	v_exp_f32_e32 v157, v157
	v_exp_f32_e32 v158, v158
	v_exp_f32_e32 v159, v159
	v_add_u32_e32 v170, 0x30, v148
	v_mad_i64_i32 v[168:169], s[4:5], v170, s70, v[140:141]
	v_pk_add_f32 v[152:153], v[152:153], 1.0 op_sel_hi:[1,0]
	v_pk_add_f32 v[154:155], v[154:155], 1.0 op_sel_hi:[1,0]
	v_pk_add_f32 v[156:157], v[156:157], 1.0 op_sel_hi:[1,0]
	v_pk_add_f32 v[158:159], v[158:159], 1.0 op_sel_hi:[1,0]
	v_rcp_f32_e32 v152, v152
	v_rcp_f32_e32 v153, v153
	v_rcp_f32_e32 v154, v154
	v_rcp_f32_e32 v155, v155
	v_rcp_f32_e32 v156, v156
	v_rcp_f32_e32 v157, v157
	v_rcp_f32_e32 v158, v158
	v_rcp_f32_e32 v159, v159
	v_lshl_add_u64 v[168:169], v[168:169], 0, v[142:143]
	v_pk_mul_f32 v[152:153], v[78:79], v[152:153]
	v_pk_mul_f32 v[154:155], v[80:81], v[154:155]
	v_pk_mul_f32 v[156:157], v[70:71], v[156:157]
	v_pk_mul_f32 v[158:159], v[72:73], v[158:159]
	v_pk_mul_f32 v[152:153], v[152:153], v[74:75]
	v_pk_mul_f32 v[154:155], v[154:155], v[76:77]
	v_pk_mul_f32 v[156:157], v[156:157], v[66:67]
	v_pk_mul_f32 v[158:159], v[158:159], v[68:69]
	v_cvt_pk_bf16_f32 v164, v152, v153
	v_cvt_pk_bf16_f32 v165, v154, v155
	v_cvt_pk_bf16_f32 v166, v156, v157
	v_cvt_pk_bf16_f32 v167, v158, v159
	global_store_dwordx4 v[168:169], v[164:167], off
	v_pk_mul_f32 v[152:153], v[62:63], s[98:99] op_sel_hi:[1,0]
	v_pk_mul_f32 v[154:155], v[64:65], s[98:99] op_sel_hi:[1,0]
	v_pk_mul_f32 v[156:157], v[54:55], s[98:99] op_sel_hi:[1,0]
	v_pk_mul_f32 v[158:159], v[56:57], s[98:99] op_sel_hi:[1,0]
	v_exp_f32_e32 v152, v152
	v_exp_f32_e32 v153, v153
	v_exp_f32_e32 v154, v154
	v_exp_f32_e32 v155, v155
	v_exp_f32_e32 v156, v156
	v_exp_f32_e32 v157, v157
	v_exp_f32_e32 v158, v158
	v_exp_f32_e32 v159, v159
	v_add_u32_e32 v170, 0x80, v148
	v_mad_i64_i32 v[168:169], s[4:5], v170, s70, v[140:141]
	v_pk_add_f32 v[152:153], v[152:153], 1.0 op_sel_hi:[1,0]
	v_pk_add_f32 v[154:155], v[154:155], 1.0 op_sel_hi:[1,0]
	v_pk_add_f32 v[156:157], v[156:157], 1.0 op_sel_hi:[1,0]
	v_pk_add_f32 v[158:159], v[158:159], 1.0 op_sel_hi:[1,0]
	v_rcp_f32_e32 v152, v152
	v_rcp_f32_e32 v153, v153
	v_rcp_f32_e32 v154, v154
	v_rcp_f32_e32 v155, v155
	v_rcp_f32_e32 v156, v156
	v_rcp_f32_e32 v157, v157
	v_rcp_f32_e32 v158, v158
	v_rcp_f32_e32 v159, v159
	v_lshl_add_u64 v[168:169], v[168:169], 0, v[142:143]
	v_pk_mul_f32 v[152:153], v[62:63], v[152:153]
	v_pk_mul_f32 v[154:155], v[64:65], v[154:155]
	v_pk_mul_f32 v[156:157], v[54:55], v[156:157]
	v_pk_mul_f32 v[158:159], v[56:57], v[158:159]
	v_pk_mul_f32 v[152:153], v[152:153], v[58:59]
	v_pk_mul_f32 v[154:155], v[154:155], v[60:61]
	v_pk_mul_f32 v[156:157], v[156:157], v[50:51]
	v_pk_mul_f32 v[158:159], v[158:159], v[52:53]
	v_cvt_pk_bf16_f32 v160, v152, v153
	v_cvt_pk_bf16_f32 v161, v154, v155
	v_cvt_pk_bf16_f32 v162, v156, v157
	v_cvt_pk_bf16_f32 v163, v158, v159
	global_store_dwordx4 v[168:169], v[160:163], off
	v_pk_mul_f32 v[152:153], v[46:47], s[98:99] op_sel_hi:[1,0]
	v_pk_mul_f32 v[154:155], v[48:49], s[98:99] op_sel_hi:[1,0]
	v_pk_mul_f32 v[156:157], v[38:39], s[98:99] op_sel_hi:[1,0]
	v_pk_mul_f32 v[158:159], v[40:41], s[98:99] op_sel_hi:[1,0]
	v_exp_f32_e32 v152, v152
	v_exp_f32_e32 v153, v153
	v_exp_f32_e32 v154, v154
	v_exp_f32_e32 v155, v155
	v_exp_f32_e32 v156, v156
	v_exp_f32_e32 v157, v157
	v_exp_f32_e32 v158, v158
	v_exp_f32_e32 v159, v159
	v_add_u32_e32 v170, 0x90, v148
	v_mad_i64_i32 v[168:169], s[4:5], v170, s70, v[140:141]
	v_pk_add_f32 v[152:153], v[152:153], 1.0 op_sel_hi:[1,0]
	v_pk_add_f32 v[154:155], v[154:155], 1.0 op_sel_hi:[1,0]
	v_pk_add_f32 v[156:157], v[156:157], 1.0 op_sel_hi:[1,0]
	v_pk_add_f32 v[158:159], v[158:159], 1.0 op_sel_hi:[1,0]
	v_rcp_f32_e32 v152, v152
	v_rcp_f32_e32 v153, v153
	v_rcp_f32_e32 v154, v154
	v_rcp_f32_e32 v155, v155
	v_rcp_f32_e32 v156, v156
	v_rcp_f32_e32 v157, v157
	v_rcp_f32_e32 v158, v158
	v_rcp_f32_e32 v159, v159
	v_lshl_add_u64 v[168:169], v[168:169], 0, v[142:143]
	v_pk_mul_f32 v[152:153], v[46:47], v[152:153]
	v_pk_mul_f32 v[154:155], v[48:49], v[154:155]
	v_pk_mul_f32 v[156:157], v[38:39], v[156:157]
	v_pk_mul_f32 v[158:159], v[40:41], v[158:159]
	v_pk_mul_f32 v[152:153], v[152:153], v[42:43]
	v_pk_mul_f32 v[154:155], v[154:155], v[44:45]
	v_pk_mul_f32 v[156:157], v[156:157], v[34:35]
	v_pk_mul_f32 v[158:159], v[158:159], v[36:37]
	v_cvt_pk_bf16_f32 v164, v152, v153
	v_cvt_pk_bf16_f32 v165, v154, v155
	v_cvt_pk_bf16_f32 v166, v156, v157
	v_cvt_pk_bf16_f32 v167, v158, v159
	global_store_dwordx4 v[168:169], v[164:167], off
	v_pk_mul_f32 v[152:153], v[30:31], s[98:99] op_sel_hi:[1,0]
	v_pk_mul_f32 v[154:155], v[32:33], s[98:99] op_sel_hi:[1,0]
	v_pk_mul_f32 v[156:157], v[22:23], s[98:99] op_sel_hi:[1,0]
	v_pk_mul_f32 v[158:159], v[24:25], s[98:99] op_sel_hi:[1,0]
	v_exp_f32_e32 v152, v152
	v_exp_f32_e32 v153, v153
	v_exp_f32_e32 v154, v154
	v_exp_f32_e32 v155, v155
	v_exp_f32_e32 v156, v156
	v_exp_f32_e32 v157, v157
	v_exp_f32_e32 v158, v158
	v_exp_f32_e32 v159, v159
	v_add_u32_e32 v170, 0xa0, v148
	v_mad_i64_i32 v[168:169], s[4:5], v170, s70, v[140:141]
	v_pk_add_f32 v[152:153], v[152:153], 1.0 op_sel_hi:[1,0]
	v_pk_add_f32 v[154:155], v[154:155], 1.0 op_sel_hi:[1,0]
	v_pk_add_f32 v[156:157], v[156:157], 1.0 op_sel_hi:[1,0]
	v_pk_add_f32 v[158:159], v[158:159], 1.0 op_sel_hi:[1,0]
	v_rcp_f32_e32 v152, v152
	v_rcp_f32_e32 v153, v153
	v_rcp_f32_e32 v154, v154
	v_rcp_f32_e32 v155, v155
	v_rcp_f32_e32 v156, v156
	v_rcp_f32_e32 v157, v157
	v_rcp_f32_e32 v158, v158
	v_rcp_f32_e32 v159, v159
	v_lshl_add_u64 v[168:169], v[168:169], 0, v[142:143]
	v_pk_mul_f32 v[152:153], v[30:31], v[152:153]
	v_pk_mul_f32 v[154:155], v[32:33], v[154:155]
	v_pk_mul_f32 v[156:157], v[22:23], v[156:157]
	v_pk_mul_f32 v[158:159], v[24:25], v[158:159]
	v_pk_mul_f32 v[152:153], v[152:153], v[26:27]
	v_pk_mul_f32 v[154:155], v[154:155], v[28:29]
	v_pk_mul_f32 v[156:157], v[156:157], v[18:19]
	v_pk_mul_f32 v[158:159], v[158:159], v[20:21]
	v_cvt_pk_bf16_f32 v160, v152, v153
	v_cvt_pk_bf16_f32 v161, v154, v155
	v_cvt_pk_bf16_f32 v162, v156, v157
	v_cvt_pk_bf16_f32 v163, v158, v159
	global_store_dwordx4 v[168:169], v[160:163], off
	v_pk_mul_f32 v[152:153], v[14:15], s[98:99] op_sel_hi:[1,0]
	v_pk_mul_f32 v[154:155], v[16:17], s[98:99] op_sel_hi:[1,0]
	v_pk_mul_f32 v[156:157], v[6:7], s[98:99] op_sel_hi:[1,0]
	v_pk_mul_f32 v[158:159], v[8:9], s[98:99] op_sel_hi:[1,0]
	v_exp_f32_e32 v152, v152
	v_exp_f32_e32 v153, v153
	v_exp_f32_e32 v154, v154
	v_exp_f32_e32 v155, v155
	v_exp_f32_e32 v156, v156
	v_exp_f32_e32 v157, v157
	v_exp_f32_e32 v158, v158
	v_exp_f32_e32 v159, v159
	v_add_u32_e32 v170, 0xb0, v148
	v_mad_i64_i32 v[168:169], s[4:5], v170, s70, v[140:141]
	v_pk_add_f32 v[152:153], v[152:153], 1.0 op_sel_hi:[1,0]
	v_pk_add_f32 v[154:155], v[154:155], 1.0 op_sel_hi:[1,0]
	v_pk_add_f32 v[156:157], v[156:157], 1.0 op_sel_hi:[1,0]
	v_pk_add_f32 v[158:159], v[158:159], 1.0 op_sel_hi:[1,0]
	v_rcp_f32_e32 v152, v152
	v_rcp_f32_e32 v153, v153
	v_rcp_f32_e32 v154, v154
	v_rcp_f32_e32 v155, v155
	v_rcp_f32_e32 v156, v156
	v_rcp_f32_e32 v157, v157
	v_rcp_f32_e32 v158, v158
	v_rcp_f32_e32 v159, v159
	v_lshl_add_u64 v[168:169], v[168:169], 0, v[142:143]
	v_pk_mul_f32 v[152:153], v[14:15], v[152:153]
	v_pk_mul_f32 v[154:155], v[16:17], v[154:155]
	v_pk_mul_f32 v[156:157], v[6:7], v[156:157]
	v_pk_mul_f32 v[158:159], v[8:9], v[158:159]
	v_pk_mul_f32 v[152:153], v[152:153], v[10:11]
	v_pk_mul_f32 v[154:155], v[154:155], v[12:13]
	v_pk_mul_f32 v[156:157], v[156:157], v[2:3]
	v_pk_mul_f32 v[158:159], v[158:159], v[4:5]
	v_cvt_pk_bf16_f32 v164, v152, v153
	v_cvt_pk_bf16_f32 v165, v154, v155
	v_cvt_pk_bf16_f32 v166, v156, v157
	v_cvt_pk_bf16_f32 v167, v158, v159
	s_mov_b64 s[4:5], -1
	global_store_dwordx4 v[168:169], v[164:167], off
	s_cbranch_vccnz .LBB0_931
	s_andn2_b64 vcc, exec, s[10:11]
	s_cbranch_vccnz .LBB0_930
	s_barrier
	s_branch .LBB0_930
